# merge-gate stream in the MERGE epilogue read with non-temporal loads
# baseline (speedup 1.0000x reference)
.LBB0_357:
	s_add_i32 s43, 0, 0x10000
	v_add_u32_e32 v128, s43, v151
	ds_read_b128 v[130:133], v128
	ds_read_b128 v[138:141], v128 offset:1024
	ds_read_b128 v[142:145], v128 offset:2048
	ds_read_b128 v[154:157], v128 offset:3072
	s_add_u32 s22, s10, s6
	v_mov_b32_e32 v188, v146
	v_mov_b32_e32 v134, v148
	s_addc_u32 s23, s11, s7
	ds_read_b128 v[158:161], v153
	ds_read_b128 v[162:165], v153 offset:1024
	ds_read_b128 v[166:169], v153 offset:2048
	ds_read_b128 v[170:173], v153 offset:3072
	ds_read_b128 v[174:177], v153 offset:4096
	ds_read_b128 v[178:181], v153 offset:5120
	ds_read_b128 v[182:185], v153 offset:6144
	ds_read_b128 v[190:193], v153 offset:7168
	s_add_i32 s15, s30, 0xc000
	v_lshl_add_u64 v[186:187], s[22:23], 0, v[188:189]
	v_mov_b32_e32 v135, v189
	v_lshl_add_u64 v[186:187], v[186:187], 0, s[50:51]
	s_mov_b32 m0, s15
	v_lshl_add_u64 v[134:135], s[22:23], 0, v[134:135]
	s_add_i32 s17, s30, 0xe000
	global_load_lds_dwordx4 v[186:187], off
	v_lshl_add_u64 v[134:135], v[134:135], 0, s[50:51]
	s_mov_b32 m0, s17
	s_nop 0
	global_load_lds_dwordx4 v[134:135], off
	s_waitcnt lgkmcnt(8)
	s_barrier
	s_waitcnt lgkmcnt(0)
	s_waitcnt lgkmcnt(0)
	v_mfma_f32_16x16x32_bf16 v[4:7], v[130:133], v[158:161], v[4:7]
	v_mfma_f32_16x16x32_bf16 v[0:3], v[142:145], v[158:161], v[0:3]
	v_mfma_f32_16x16x32_bf16 v[20:23], v[130:133], v[166:169], v[20:23]
	v_mfma_f32_16x16x32_bf16 v[16:19], v[142:145], v[166:169], v[16:19]
	v_mfma_f32_16x16x32_bf16 v[36:39], v[130:133], v[174:177], v[36:39]
	v_mfma_f32_16x16x32_bf16 v[32:35], v[142:145], v[174:177], v[32:35]
	v_mfma_f32_16x16x32_bf16 v[52:55], v[130:133], v[182:185], v[52:55]
	v_mfma_f32_16x16x32_bf16 v[48:51], v[142:145], v[182:185], v[48:51]
	v_mfma_f32_16x16x32_bf16 v[4:7], v[138:141], v[162:165], v[4:7]
	v_mfma_f32_16x16x32_bf16 v[0:3], v[154:157], v[162:165], v[0:3]
	v_mfma_f32_16x16x32_bf16 v[20:23], v[138:141], v[170:173], v[20:23]
	v_mfma_f32_16x16x32_bf16 v[16:19], v[154:157], v[170:173], v[16:19]
	v_mfma_f32_16x16x32_bf16 v[36:39], v[138:141], v[178:181], v[36:39]
	v_mfma_f32_16x16x32_bf16 v[32:35], v[154:157], v[178:181], v[32:35]
	v_mfma_f32_16x16x32_bf16 v[52:55], v[138:141], v[190:193], v[52:55]
	v_mfma_f32_16x16x32_bf16 v[48:51], v[154:157], v[190:193], v[48:51]
	s_barrier
	s_add_i32 s45, 0, 0x14000
	s_add_u32 s24, s8, s6
	v_add_u32_e32 v129, s45, v151
	v_mov_b32_e32 v188, v147
	v_mov_b32_e32 v134, v149
	s_addc_u32 s25, s9, s7
	ds_read_b128 v[202:205], v129
	ds_read_b128 v[222:225], v129 offset:1024
	ds_read_b128 v[226:229], v129 offset:2048
	ds_read_b128 v[230:233], v129 offset:3072
	s_add_i32 s43, s43, s29
	v_lshl_add_u64 v[186:187], s[24:25], 0, v[188:189]
	v_mov_b32_e32 v135, v189
	v_lshl_add_u64 v[186:187], v[186:187], 0, s[88:89]
	s_mov_b32 m0, s43
	v_lshl_add_u64 v[134:135], s[24:25], 0, v[134:135]
	s_add_i32 s44, s43, 0x2000
	global_load_lds_dwordx4 v[186:187], off
	v_lshl_add_u64 v[134:135], v[134:135], 0, s[88:89]
	s_mov_b32 m0, s44
	s_nop 0
	global_load_lds_dwordx4 v[134:135], off
	s_barrier
	s_waitcnt lgkmcnt(0)
	s_waitcnt lgkmcnt(0)
	v_mfma_f32_16x16x32_bf16 v[12:15], v[202:205], v[158:161], v[12:15]
	v_mfma_f32_16x16x32_bf16 v[8:11], v[226:229], v[158:161], v[8:11]
	v_mfma_f32_16x16x32_bf16 v[28:31], v[202:205], v[166:169], v[28:31]
	v_mfma_f32_16x16x32_bf16 v[24:27], v[226:229], v[166:169], v[24:27]
	v_mfma_f32_16x16x32_bf16 v[44:47], v[202:205], v[174:177], v[44:47]
	v_mfma_f32_16x16x32_bf16 v[40:43], v[226:229], v[174:177], v[40:43]
	v_mfma_f32_16x16x32_bf16 v[60:63], v[202:205], v[182:185], v[60:63]
	v_mfma_f32_16x16x32_bf16 v[56:59], v[226:229], v[182:185], v[56:59]
	v_mfma_f32_16x16x32_bf16 v[12:15], v[222:225], v[162:165], v[12:15]
	v_mfma_f32_16x16x32_bf16 v[8:11], v[230:233], v[162:165], v[8:11]
	v_mfma_f32_16x16x32_bf16 v[28:31], v[222:225], v[170:173], v[28:31]
	v_mfma_f32_16x16x32_bf16 v[24:27], v[230:233], v[170:173], v[24:27]
	v_mfma_f32_16x16x32_bf16 v[44:47], v[222:225], v[178:181], v[44:47]
	v_mfma_f32_16x16x32_bf16 v[40:43], v[230:233], v[178:181], v[40:43]
	v_mfma_f32_16x16x32_bf16 v[60:63], v[222:225], v[190:193], v[60:63]
	v_mfma_f32_16x16x32_bf16 v[56:59], v[230:233], v[190:193], v[56:59]
	v_mov_b32_e32 v188, v146
	v_mov_b32_e32 v134, v148
	s_barrier
	ds_read_b128 v[158:161], v153 offset:16384
	ds_read_b128 v[162:165], v153 offset:17408
	ds_read_b128 v[166:169], v153 offset:18432
	ds_read_b128 v[170:173], v153 offset:19456
	ds_read_b128 v[174:177], v153 offset:20480
	ds_read_b128 v[178:181], v153 offset:21504
	ds_read_b128 v[182:185], v153 offset:22528
	ds_read_b128 v[190:193], v153 offset:23552
	v_mov_b32_e32 v135, v189
	v_lshl_add_u64 v[186:187], s[22:23], 0, v[188:189]
	s_mov_b32 m0, s30
	v_lshl_add_u64 v[186:187], v[186:187], 0, s[88:89]
	v_lshl_add_u64 v[134:135], s[22:23], 0, v[134:135]
	global_load_lds_dwordx4 v[186:187], off
	v_lshl_add_u64 v[134:135], v[134:135], 0, s[88:89]
	s_mov_b32 m0, s31
	s_nop 0
	global_load_lds_dwordx4 v[134:135], off
	s_barrier
	s_waitcnt lgkmcnt(0)
	s_waitcnt lgkmcnt(0)
	v_mfma_f32_16x16x32_bf16 v[68:71], v[130:133], v[158:161], v[68:71]
	v_mfma_f32_16x16x32_bf16 v[64:67], v[142:145], v[158:161], v[64:67]
	v_mfma_f32_16x16x32_bf16 v[84:87], v[130:133], v[166:169], v[84:87]
	v_mfma_f32_16x16x32_bf16 v[80:83], v[142:145], v[166:169], v[80:83]
	v_mfma_f32_16x16x32_bf16 v[100:103], v[130:133], v[174:177], v[100:103]
	v_mfma_f32_16x16x32_bf16 v[96:99], v[142:145], v[174:177], v[96:99]
	v_mfma_f32_16x16x32_bf16 v[120:123], v[130:133], v[182:185], v[120:123]
	v_mfma_f32_16x16x32_bf16 v[116:119], v[142:145], v[182:185], v[116:119]
	v_mfma_f32_16x16x32_bf16 v[68:71], v[138:141], v[162:165], v[68:71]
	v_mfma_f32_16x16x32_bf16 v[64:67], v[154:157], v[162:165], v[64:67]
	v_mfma_f32_16x16x32_bf16 v[84:87], v[138:141], v[170:173], v[84:87]
	v_mfma_f32_16x16x32_bf16 v[80:83], v[154:157], v[170:173], v[80:83]
	v_mfma_f32_16x16x32_bf16 v[100:103], v[138:141], v[178:181], v[100:103]
	v_mfma_f32_16x16x32_bf16 v[96:99], v[154:157], v[178:181], v[96:99]
	v_mfma_f32_16x16x32_bf16 v[120:123], v[138:141], v[190:193], v[120:123]
	v_mfma_f32_16x16x32_bf16 v[116:119], v[154:157], v[190:193], v[116:119]
	s_barrier
	v_mov_b32_e32 v188, v147
	v_mov_b32_e32 v130, v149
	s_add_i32 s45, s45, s29
	v_lshl_add_u64 v[132:133], s[24:25], 0, v[188:189]
	v_mov_b32_e32 v131, v189
	v_lshl_add_u64 v[132:133], v[132:133], 0, s[52:53]
	s_mov_b32 m0, s45
	v_lshl_add_u64 v[130:131], s[24:25], 0, v[130:131]
	s_add_i32 s46, s45, 0x2000
	global_load_lds_dwordx4 v[132:133], off
	v_lshl_add_u64 v[130:131], v[130:131], 0, s[52:53]
	s_mov_b32 m0, s46
	s_nop 0
	global_load_lds_dwordx4 v[130:131], off
	s_waitcnt vmcnt(6)
	s_barrier
	v_mfma_f32_16x16x32_bf16 v[76:79], v[202:205], v[158:161], v[76:79]
	v_mfma_f32_16x16x32_bf16 v[72:75], v[226:229], v[158:161], v[72:75]
	v_mfma_f32_16x16x32_bf16 v[92:95], v[202:205], v[166:169], v[92:95]
	v_mfma_f32_16x16x32_bf16 v[88:91], v[226:229], v[166:169], v[88:91]
	v_mfma_f32_16x16x32_bf16 v[108:111], v[202:205], v[174:177], v[108:111]
	v_mfma_f32_16x16x32_bf16 v[104:107], v[226:229], v[174:177], v[104:107]
	v_mfma_f32_16x16x32_bf16 v[124:127], v[202:205], v[182:185], v[124:127]
	v_mfma_f32_16x16x32_bf16 v[112:115], v[226:229], v[182:185], v[112:115]
	v_mfma_f32_16x16x32_bf16 v[76:79], v[222:225], v[162:165], v[76:79]
	v_mfma_f32_16x16x32_bf16 v[72:75], v[230:233], v[162:165], v[72:75]
	v_mfma_f32_16x16x32_bf16 v[92:95], v[222:225], v[170:173], v[92:95]
	v_mfma_f32_16x16x32_bf16 v[88:91], v[230:233], v[170:173], v[88:91]
	v_mfma_f32_16x16x32_bf16 v[108:111], v[222:225], v[178:181], v[108:111]
	v_mfma_f32_16x16x32_bf16 v[104:107], v[230:233], v[178:181], v[104:107]
	v_mfma_f32_16x16x32_bf16 v[124:127], v[222:225], v[190:193], v[124:127]
	v_mfma_f32_16x16x32_bf16 v[112:115], v[230:233], v[190:193], v[112:115]
	s_add_i32 s48, 0, 0x18000
	v_add_u32_e32 v130, s48, v151
	s_barrier
	ds_read_b128 v[132:135], v130
	ds_read_b128 v[138:141], v130 offset:1024
	ds_read_b128 v[142:145], v130 offset:2048
	ds_read_b128 v[154:157], v130 offset:3072
	v_mov_b32_e32 v188, v146
	v_mov_b32_e32 v186, v148
	ds_read_b128 v[158:161], v153 offset:32768
	ds_read_b128 v[162:165], v153 offset:33792
	ds_read_b128 v[166:169], v153 offset:34816
	ds_read_b128 v[170:173], v153 offset:35840
	ds_read_b128 v[174:177], v153 offset:36864
	ds_read_b128 v[178:181], v153 offset:37888
	ds_read_b128 v[182:185], v153 offset:38912
	ds_read_b128 v[190:193], v153 offset:39936
	v_mov_b32_e32 v187, v189
	v_lshl_add_u64 v[194:195], s[22:23], 0, v[188:189]
	s_mov_b32 m0, s34
	v_lshl_add_u64 v[194:195], v[194:195], 0, s[52:53]
	v_lshl_add_u64 v[186:187], s[22:23], 0, v[186:187]
	global_load_lds_dwordx4 v[194:195], off
	v_lshl_add_u64 v[186:187], v[186:187], 0, s[52:53]
	s_mov_b32 m0, s35
	s_nop 0
	global_load_lds_dwordx4 v[186:187], off
	s_waitcnt lgkmcnt(8)
	s_barrier
	s_waitcnt lgkmcnt(0)
	s_waitcnt lgkmcnt(0)
	v_mfma_f32_16x16x32_bf16 v[4:7], v[132:135], v[158:161], v[4:7]
	v_mfma_f32_16x16x32_bf16 v[0:3], v[142:145], v[158:161], v[0:3]
	v_mfma_f32_16x16x32_bf16 v[20:23], v[132:135], v[166:169], v[20:23]
	v_mfma_f32_16x16x32_bf16 v[16:19], v[142:145], v[166:169], v[16:19]
	v_mfma_f32_16x16x32_bf16 v[36:39], v[132:135], v[174:177], v[36:39]
	v_mfma_f32_16x16x32_bf16 v[32:35], v[142:145], v[174:177], v[32:35]
	v_mfma_f32_16x16x32_bf16 v[52:55], v[132:135], v[182:185], v[52:55]
	v_mfma_f32_16x16x32_bf16 v[48:51], v[142:145], v[182:185], v[48:51]
	v_mfma_f32_16x16x32_bf16 v[4:7], v[138:141], v[162:165], v[4:7]
	v_mfma_f32_16x16x32_bf16 v[0:3], v[154:157], v[162:165], v[0:3]
	v_mfma_f32_16x16x32_bf16 v[20:23], v[138:141], v[170:173], v[20:23]
	v_mfma_f32_16x16x32_bf16 v[16:19], v[154:157], v[170:173], v[16:19]
	v_mfma_f32_16x16x32_bf16 v[36:39], v[138:141], v[178:181], v[36:39]
	v_mfma_f32_16x16x32_bf16 v[32:35], v[154:157], v[178:181], v[32:35]
	v_mfma_f32_16x16x32_bf16 v[52:55], v[138:141], v[190:193], v[52:55]
	v_mfma_f32_16x16x32_bf16 v[48:51], v[154:157], v[190:193], v[48:51]
	s_barrier
	s_add_i32 s49, 0, 0x1c000
	v_add_u32_e32 v131, s49, v151
	v_mov_b32_e32 v188, v147
	v_mov_b32_e32 v186, v149
	ds_read_b128 v[202:205], v131
	ds_read_b128 v[222:225], v131 offset:1024
	ds_read_b128 v[226:229], v131 offset:2048
	ds_read_b128 v[230:233], v131 offset:3072
	s_add_i32 s48, s48, s29
	v_lshl_add_u64 v[194:195], s[24:25], 0, v[188:189]
	v_mov_b32_e32 v187, v189
	v_lshl_add_u64 v[194:195], v[194:195], 0, s[2:3]
	s_mov_b32 m0, s48
	v_lshl_add_u64 v[186:187], s[24:25], 0, v[186:187]
	s_add_i32 s47, s48, 0x2000
	global_load_lds_dwordx4 v[194:195], off
	v_lshl_add_u64 v[186:187], v[186:187], 0, s[2:3]
	s_mov_b32 m0, s47
	s_nop 0
	global_load_lds_dwordx4 v[186:187], off
	s_barrier
	s_waitcnt lgkmcnt(0)
	s_waitcnt lgkmcnt(0)
	v_mfma_f32_16x16x32_bf16 v[12:15], v[202:205], v[158:161], v[12:15]
	v_mfma_f32_16x16x32_bf16 v[8:11], v[226:229], v[158:161], v[8:11]
	v_mfma_f32_16x16x32_bf16 v[28:31], v[202:205], v[166:169], v[28:31]
	v_mfma_f32_16x16x32_bf16 v[24:27], v[226:229], v[166:169], v[24:27]
	v_mfma_f32_16x16x32_bf16 v[44:47], v[202:205], v[174:177], v[44:47]
	v_mfma_f32_16x16x32_bf16 v[40:43], v[226:229], v[174:177], v[40:43]
	v_mfma_f32_16x16x32_bf16 v[60:63], v[202:205], v[182:185], v[60:63]
	v_mfma_f32_16x16x32_bf16 v[56:59], v[226:229], v[182:185], v[56:59]
	v_mfma_f32_16x16x32_bf16 v[12:15], v[222:225], v[162:165], v[12:15]
	v_mfma_f32_16x16x32_bf16 v[8:11], v[230:233], v[162:165], v[8:11]
	v_mfma_f32_16x16x32_bf16 v[28:31], v[222:225], v[170:173], v[28:31]
	v_mfma_f32_16x16x32_bf16 v[24:27], v[230:233], v[170:173], v[24:27]
	v_mfma_f32_16x16x32_bf16 v[44:47], v[222:225], v[178:181], v[44:47]
	v_mfma_f32_16x16x32_bf16 v[40:43], v[230:233], v[178:181], v[40:43]
	v_mfma_f32_16x16x32_bf16 v[60:63], v[222:225], v[190:193], v[60:63]
	v_mfma_f32_16x16x32_bf16 v[56:59], v[230:233], v[190:193], v[56:59]
	v_mov_b32_e32 v188, v146
	v_mov_b32_e32 v186, v148
	s_barrier
	ds_read_b128 v[158:161], v153 offset:49152
	ds_read_b128 v[162:165], v153 offset:50176
	ds_read_b128 v[166:169], v153 offset:51200
	ds_read_b128 v[170:173], v153 offset:52224
	ds_read_b128 v[174:177], v153 offset:53248
	ds_read_b128 v[178:181], v153 offset:54272
	ds_read_b128 v[182:185], v153 offset:55296
	ds_read_b128 v[190:193], v153 offset:56320
	v_mov_b32_e32 v187, v189
	v_lshl_add_u64 v[194:195], s[22:23], 0, v[188:189]
	s_mov_b32 m0, s36
	v_lshl_add_u64 v[194:195], v[194:195], 0, s[2:3]
	v_lshl_add_u64 v[186:187], s[22:23], 0, v[186:187]
	global_load_lds_dwordx4 v[194:195], off
	v_lshl_add_u64 v[186:187], v[186:187], 0, s[2:3]
	s_mov_b32 m0, s37
	s_nop 0
	global_load_lds_dwordx4 v[186:187], off
	s_barrier
	s_waitcnt lgkmcnt(0)
	s_waitcnt lgkmcnt(0)
	v_mfma_f32_16x16x32_bf16 v[68:71], v[132:135], v[158:161], v[68:71]
	v_mfma_f32_16x16x32_bf16 v[64:67], v[142:145], v[158:161], v[64:67]
	v_mfma_f32_16x16x32_bf16 v[84:87], v[132:135], v[166:169], v[84:87]
	v_mfma_f32_16x16x32_bf16 v[80:83], v[142:145], v[166:169], v[80:83]
	v_mfma_f32_16x16x32_bf16 v[100:103], v[132:135], v[174:177], v[100:103]
	v_mfma_f32_16x16x32_bf16 v[96:99], v[142:145], v[174:177], v[96:99]
	v_mfma_f32_16x16x32_bf16 v[120:123], v[132:135], v[182:185], v[120:123]
	v_mfma_f32_16x16x32_bf16 v[116:119], v[142:145], v[182:185], v[116:119]
	v_mfma_f32_16x16x32_bf16 v[68:71], v[138:141], v[162:165], v[68:71]
	v_mfma_f32_16x16x32_bf16 v[64:67], v[154:157], v[162:165], v[64:67]
	v_mfma_f32_16x16x32_bf16 v[84:87], v[138:141], v[170:173], v[84:87]
	v_mfma_f32_16x16x32_bf16 v[80:83], v[154:157], v[170:173], v[80:83]
	v_mfma_f32_16x16x32_bf16 v[100:103], v[138:141], v[178:181], v[100:103]
	v_mfma_f32_16x16x32_bf16 v[96:99], v[154:157], v[178:181], v[96:99]
	v_mfma_f32_16x16x32_bf16 v[120:123], v[138:141], v[190:193], v[120:123]
	v_mfma_f32_16x16x32_bf16 v[116:119], v[154:157], v[190:193], v[116:119]
	s_barrier
	v_mov_b32_e32 v188, v147
	v_mov_b32_e32 v132, v149
	s_add_i32 s22, s49, s29
	v_lshl_add_u64 v[134:135], s[24:25], 0, v[188:189]
	v_mov_b32_e32 v133, v189
	v_lshl_add_u64 v[134:135], v[134:135], 0, s[54:55]
	s_mov_b32 m0, s22
	v_lshl_add_u64 v[132:133], s[24:25], 0, v[132:133]
	s_add_i32 s23, s22, 0x2000
	global_load_lds_dwordx4 v[134:135], off
	v_lshl_add_u64 v[132:133], v[132:133], 0, s[54:55]
	s_mov_b32 m0, s23
	s_nop 0
	global_load_lds_dwordx4 v[132:133], off
	s_waitcnt vmcnt(6)
	s_barrier
	v_mfma_f32_16x16x32_bf16 v[76:79], v[202:205], v[158:161], v[76:79]
	v_mfma_f32_16x16x32_bf16 v[72:75], v[226:229], v[158:161], v[72:75]
	v_mfma_f32_16x16x32_bf16 v[92:95], v[202:205], v[166:169], v[92:95]
	v_mfma_f32_16x16x32_bf16 v[88:91], v[226:229], v[166:169], v[88:91]
	v_mfma_f32_16x16x32_bf16 v[108:111], v[202:205], v[174:177], v[108:111]
	v_mfma_f32_16x16x32_bf16 v[104:107], v[226:229], v[174:177], v[104:107]
	v_mfma_f32_16x16x32_bf16 v[124:127], v[202:205], v[182:185], v[124:127]
	v_mfma_f32_16x16x32_bf16 v[112:115], v[226:229], v[182:185], v[112:115]
	v_mfma_f32_16x16x32_bf16 v[76:79], v[222:225], v[162:165], v[76:79]
	v_mfma_f32_16x16x32_bf16 v[72:75], v[230:233], v[162:165], v[72:75]
	v_mfma_f32_16x16x32_bf16 v[92:95], v[222:225], v[170:173], v[92:95]
	v_mfma_f32_16x16x32_bf16 v[88:91], v[230:233], v[170:173], v[88:91]
	v_mfma_f32_16x16x32_bf16 v[108:111], v[222:225], v[178:181], v[108:111]
	v_mfma_f32_16x16x32_bf16 v[104:107], v[230:233], v[178:181], v[104:107]
	v_mfma_f32_16x16x32_bf16 v[124:127], v[222:225], v[190:193], v[124:127]
	v_mfma_f32_16x16x32_bf16 v[112:115], v[230:233], v[190:193], v[112:115]
	s_add_i32 s13, s13, 2
	s_add_u32 s6, s6, 0x100
	s_addc_u32 s7, s7, 0
	s_cmp_lt_u32 s13, 4
	s_barrier
	s_cbranch_scc1 .LBB0_357
	ds_read_b128 v[132:135], v128
	ds_read_b128 v[138:141], v128 offset:1024
	ds_read_b128 v[142:145], v128 offset:2048
	ds_read_b128 v[154:157], v128 offset:3072
	s_add_u32 s6, s10, 0x20380
	v_mov_b32_e32 v128, v148
	v_mov_b32_e32 v186, v146
	s_addc_u32 s7, s11, 0
	s_mov_b32 m0, s15
	ds_read_b128 v[158:161], v153
	ds_read_b128 v[162:165], v153 offset:1024
	ds_read_b128 v[166:169], v153 offset:2048
	ds_read_b128 v[170:173], v153 offset:3072
	ds_read_b128 v[174:177], v153 offset:4096
	ds_read_b128 v[178:181], v153 offset:5120
	ds_read_b128 v[182:185], v153 offset:6144
	ds_read_b128 v[190:193], v153 offset:7168
	s_nop 0
	global_load_lds_dwordx4 v186, s[6:7]
	s_mov_b32 m0, s17
	s_nop 0
	global_load_lds_dwordx4 v128, s[6:7]
	s_waitcnt lgkmcnt(8)
	s_barrier
	s_waitcnt lgkmcnt(0)
	s_waitcnt lgkmcnt(0)
	v_mfma_f32_16x16x32_bf16 v[4:7], v[132:135], v[158:161], v[4:7]
	v_mfma_f32_16x16x32_bf16 v[0:3], v[142:145], v[158:161], v[0:3]
	v_mfma_f32_16x16x32_bf16 v[20:23], v[132:135], v[166:169], v[20:23]
	v_mfma_f32_16x16x32_bf16 v[16:19], v[142:145], v[166:169], v[16:19]
	v_mfma_f32_16x16x32_bf16 v[36:39], v[132:135], v[174:177], v[36:39]
	v_mfma_f32_16x16x32_bf16 v[32:35], v[142:145], v[174:177], v[32:35]
	v_mfma_f32_16x16x32_bf16 v[52:55], v[132:135], v[182:185], v[52:55]
	v_mfma_f32_16x16x32_bf16 v[48:51], v[142:145], v[182:185], v[48:51]
	v_mfma_f32_16x16x32_bf16 v[4:7], v[138:141], v[162:165], v[4:7]
	v_mfma_f32_16x16x32_bf16 v[0:3], v[154:157], v[162:165], v[0:3]
	v_mfma_f32_16x16x32_bf16 v[20:23], v[138:141], v[170:173], v[20:23]
	v_mfma_f32_16x16x32_bf16 v[16:19], v[154:157], v[170:173], v[16:19]
	v_mfma_f32_16x16x32_bf16 v[36:39], v[138:141], v[178:181], v[36:39]
	v_mfma_f32_16x16x32_bf16 v[32:35], v[154:157], v[178:181], v[32:35]
	v_mfma_f32_16x16x32_bf16 v[52:55], v[138:141], v[190:193], v[52:55]
	v_mfma_f32_16x16x32_bf16 v[48:51], v[154:157], v[190:193], v[48:51]
	s_barrier
	ds_read_b128 v[202:205], v129
	ds_read_b128 v[222:225], v129 offset:1024
	ds_read_b128 v[226:229], v129 offset:2048
	ds_read_b128 v[230:233], v129 offset:3072
	v_mov_b32_e32 v128, v149
	v_mov_b32_e32 v129, v147
	s_mov_b32 m0, s43
	s_nop 0
	global_load_lds_dwordx4 v129, s[20:21]
	s_mov_b32 m0, s44
	s_nop 0
	global_load_lds_dwordx4 v128, s[20:21]
	s_barrier
	s_waitcnt lgkmcnt(0)
	s_waitcnt lgkmcnt(0)
	v_mfma_f32_16x16x32_bf16 v[12:15], v[202:205], v[158:161], v[12:15]
	v_mfma_f32_16x16x32_bf16 v[8:11], v[226:229], v[158:161], v[8:11]
	v_mfma_f32_16x16x32_bf16 v[28:31], v[202:205], v[166:169], v[28:31]
	v_mfma_f32_16x16x32_bf16 v[24:27], v[226:229], v[166:169], v[24:27]
	v_mfma_f32_16x16x32_bf16 v[44:47], v[202:205], v[174:177], v[44:47]
	v_mfma_f32_16x16x32_bf16 v[40:43], v[226:229], v[174:177], v[40:43]
	v_mfma_f32_16x16x32_bf16 v[60:63], v[202:205], v[182:185], v[60:63]
	v_mfma_f32_16x16x32_bf16 v[56:59], v[226:229], v[182:185], v[56:59]
	v_mfma_f32_16x16x32_bf16 v[12:15], v[222:225], v[162:165], v[12:15]
	v_mfma_f32_16x16x32_bf16 v[8:11], v[230:233], v[162:165], v[8:11]
	v_mfma_f32_16x16x32_bf16 v[28:31], v[222:225], v[170:173], v[28:31]
	v_mfma_f32_16x16x32_bf16 v[24:27], v[230:233], v[170:173], v[24:27]
	v_mfma_f32_16x16x32_bf16 v[44:47], v[222:225], v[178:181], v[44:47]
	v_mfma_f32_16x16x32_bf16 v[40:43], v[230:233], v[178:181], v[40:43]
	v_mfma_f32_16x16x32_bf16 v[60:63], v[222:225], v[190:193], v[60:63]
	v_mfma_f32_16x16x32_bf16 v[56:59], v[230:233], v[190:193], v[56:59]
	v_mov_b32_e32 v128, v148
	v_mov_b32_e32 v129, v146
	s_mov_b32 m0, s30
	s_barrier
	ds_read_b128 v[158:161], v153 offset:16384
	ds_read_b128 v[162:165], v153 offset:17408
	ds_read_b128 v[166:169], v153 offset:18432
	ds_read_b128 v[170:173], v153 offset:19456
	ds_read_b128 v[174:177], v153 offset:20480
	ds_read_b128 v[178:181], v153 offset:21504
	ds_read_b128 v[182:185], v153 offset:22528
	ds_read_b128 v[190:193], v153 offset:23552
	s_nop 0
	global_load_lds_dwordx4 v129, s[18:19]
	s_mov_b32 m0, s31
	s_nop 0
	global_load_lds_dwordx4 v128, s[18:19]
	s_barrier
	s_waitcnt lgkmcnt(0)
	s_waitcnt lgkmcnt(0)
	v_mfma_f32_16x16x32_bf16 v[68:71], v[132:135], v[158:161], v[68:71]
	v_mfma_f32_16x16x32_bf16 v[64:67], v[142:145], v[158:161], v[64:67]
	v_mfma_f32_16x16x32_bf16 v[84:87], v[132:135], v[166:169], v[84:87]
	v_mfma_f32_16x16x32_bf16 v[80:83], v[142:145], v[166:169], v[80:83]
	v_mfma_f32_16x16x32_bf16 v[100:103], v[132:135], v[174:177], v[100:103]
	v_mfma_f32_16x16x32_bf16 v[96:99], v[142:145], v[174:177], v[96:99]
	v_mfma_f32_16x16x32_bf16 v[120:123], v[132:135], v[182:185], v[120:123]
	v_mfma_f32_16x16x32_bf16 v[116:119], v[142:145], v[182:185], v[116:119]
	v_mfma_f32_16x16x32_bf16 v[68:71], v[138:141], v[162:165], v[68:71]
	v_mfma_f32_16x16x32_bf16 v[64:67], v[154:157], v[162:165], v[64:67]
	v_mfma_f32_16x16x32_bf16 v[84:87], v[138:141], v[170:173], v[84:87]
	v_mfma_f32_16x16x32_bf16 v[80:83], v[154:157], v[170:173], v[80:83]
	v_mfma_f32_16x16x32_bf16 v[100:103], v[138:141], v[178:181], v[100:103]
	v_mfma_f32_16x16x32_bf16 v[96:99], v[154:157], v[178:181], v[96:99]
	v_mfma_f32_16x16x32_bf16 v[120:123], v[138:141], v[190:193], v[120:123]
	v_mfma_f32_16x16x32_bf16 v[116:119], v[154:157], v[190:193], v[116:119]
	s_barrier
	s_add_u32 s6, s20, 0x20000
	v_mov_b32_e32 v128, v149
	v_mov_b32_e32 v129, v147
	s_addc_u32 s7, s21, 0
	s_mov_b32 m0, s45
	s_nop 0
	global_load_lds_dwordx4 v129, s[6:7]
	s_mov_b32 m0, s46
	s_nop 0
	global_load_lds_dwordx4 v128, s[6:7]
	s_waitcnt vmcnt(6)
	s_barrier
	v_mfma_f32_16x16x32_bf16 v[76:79], v[202:205], v[158:161], v[76:79]
	v_mfma_f32_16x16x32_bf16 v[72:75], v[226:229], v[158:161], v[72:75]
	v_mfma_f32_16x16x32_bf16 v[92:95], v[202:205], v[166:169], v[92:95]
	v_mfma_f32_16x16x32_bf16 v[88:91], v[226:229], v[166:169], v[88:91]
	v_mfma_f32_16x16x32_bf16 v[108:111], v[202:205], v[174:177], v[108:111]
	v_mfma_f32_16x16x32_bf16 v[104:107], v[226:229], v[174:177], v[104:107]
	v_mfma_f32_16x16x32_bf16 v[124:127], v[202:205], v[182:185], v[124:127]
	v_mfma_f32_16x16x32_bf16 v[112:115], v[226:229], v[182:185], v[112:115]
	v_mfma_f32_16x16x32_bf16 v[76:79], v[222:225], v[162:165], v[76:79]
	v_mfma_f32_16x16x32_bf16 v[72:75], v[230:233], v[162:165], v[72:75]
	v_mfma_f32_16x16x32_bf16 v[92:95], v[222:225], v[170:173], v[92:95]
	v_mfma_f32_16x16x32_bf16 v[88:91], v[230:233], v[170:173], v[88:91]
	v_mfma_f32_16x16x32_bf16 v[108:111], v[222:225], v[178:181], v[108:111]
	v_mfma_f32_16x16x32_bf16 v[104:107], v[230:233], v[178:181], v[104:107]
	v_mfma_f32_16x16x32_bf16 v[124:127], v[222:225], v[190:193], v[124:127]
	v_mfma_f32_16x16x32_bf16 v[112:115], v[230:233], v[190:193], v[112:115]
	s_barrier
	ds_read_b128 v[132:135], v130
	ds_read_b128 v[138:141], v130 offset:1024
	ds_read_b128 v[142:145], v130 offset:2048
	ds_read_b128 v[154:157], v130 offset:3072
	s_add_u32 s6, s18, 0x20000
	v_mov_b32_e32 v128, v148
	v_mov_b32_e32 v129, v146
	s_addc_u32 s7, s19, 0
	s_mov_b32 m0, s34
	ds_read_b128 v[158:161], v153 offset:32768
	ds_read_b128 v[162:165], v153 offset:33792
	ds_read_b128 v[166:169], v153 offset:34816
	ds_read_b128 v[170:173], v153 offset:35840
	ds_read_b128 v[174:177], v153 offset:36864
	ds_read_b128 v[178:181], v153 offset:37888
	ds_read_b128 v[182:185], v153 offset:38912
	ds_read_b128 v[190:193], v153 offset:39936
	s_nop 0
	global_load_lds_dwordx4 v129, s[6:7]
	s_mov_b32 m0, s35
	s_nop 0
	global_load_lds_dwordx4 v128, s[6:7]
	s_waitcnt lgkmcnt(8)
	s_barrier
	s_waitcnt lgkmcnt(0)
	s_waitcnt lgkmcnt(0)
	v_mfma_f32_16x16x32_bf16 v[4:7], v[132:135], v[158:161], v[4:7]
	v_mfma_f32_16x16x32_bf16 v[0:3], v[142:145], v[158:161], v[0:3]
	v_mfma_f32_16x16x32_bf16 v[20:23], v[132:135], v[166:169], v[20:23]
	v_mfma_f32_16x16x32_bf16 v[16:19], v[142:145], v[166:169], v[16:19]
	v_mfma_f32_16x16x32_bf16 v[36:39], v[132:135], v[174:177], v[36:39]
	v_mfma_f32_16x16x32_bf16 v[32:35], v[142:145], v[174:177], v[32:35]
	v_mfma_f32_16x16x32_bf16 v[52:55], v[132:135], v[182:185], v[52:55]
	v_mfma_f32_16x16x32_bf16 v[48:51], v[142:145], v[182:185], v[48:51]
	v_mfma_f32_16x16x32_bf16 v[4:7], v[138:141], v[162:165], v[4:7]
	v_mfma_f32_16x16x32_bf16 v[0:3], v[154:157], v[162:165], v[0:3]
	v_mfma_f32_16x16x32_bf16 v[20:23], v[138:141], v[170:173], v[20:23]
	v_mfma_f32_16x16x32_bf16 v[16:19], v[154:157], v[170:173], v[16:19]
	v_mfma_f32_16x16x32_bf16 v[36:39], v[138:141], v[178:181], v[36:39]
	v_mfma_f32_16x16x32_bf16 v[32:35], v[154:157], v[178:181], v[32:35]
	v_mfma_f32_16x16x32_bf16 v[52:55], v[138:141], v[190:193], v[52:55]
	v_mfma_f32_16x16x32_bf16 v[48:51], v[154:157], v[190:193], v[48:51]
	s_barrier
	v_mov_b32_e32 v186, v149
	v_mov_b32_e32 v188, v147
	ds_read_b128 v[202:205], v131
	ds_read_b128 v[222:225], v131 offset:1024
	ds_read_b128 v[226:229], v131 offset:2048
	ds_read_b128 v[128:131], v131 offset:3072
	s_mov_b64 s[6:7], 0x80
	v_lshl_add_u64 v[194:195], s[20:21], 0, v[188:189]
	v_mov_b32_e32 v187, v189
	s_mov_b32 m0, s48
	v_lshl_add_u64 v[194:195], v[194:195], 0, s[6:7]
	v_lshl_add_u64 v[186:187], s[20:21], 0, v[186:187]
	global_load_lds_dwordx4 v[194:195], off
	v_lshl_add_u64 v[186:187], v[186:187], 0, s[6:7]
	s_mov_b32 m0, s47
	s_nop 0
	global_load_lds_dwordx4 v[186:187], off
	s_barrier
	s_waitcnt lgkmcnt(0)
	s_waitcnt lgkmcnt(0)
	v_mfma_f32_16x16x32_bf16 v[12:15], v[202:205], v[158:161], v[12:15]
	v_mfma_f32_16x16x32_bf16 v[8:11], v[226:229], v[158:161], v[8:11]
	v_mfma_f32_16x16x32_bf16 v[28:31], v[202:205], v[166:169], v[28:31]
	v_mfma_f32_16x16x32_bf16 v[24:27], v[226:229], v[166:169], v[24:27]
	v_mfma_f32_16x16x32_bf16 v[44:47], v[202:205], v[174:177], v[44:47]
	v_mfma_f32_16x16x32_bf16 v[40:43], v[226:229], v[174:177], v[40:43]
	v_mfma_f32_16x16x32_bf16 v[60:63], v[202:205], v[182:185], v[60:63]
	v_mfma_f32_16x16x32_bf16 v[56:59], v[226:229], v[182:185], v[56:59]
	v_mfma_f32_16x16x32_bf16 v[12:15], v[222:225], v[162:165], v[12:15]
	v_mfma_f32_16x16x32_bf16 v[8:11], v[128:131], v[162:165], v[8:11]
	v_mfma_f32_16x16x32_bf16 v[28:31], v[222:225], v[170:173], v[28:31]
	v_mfma_f32_16x16x32_bf16 v[24:27], v[128:131], v[170:173], v[24:27]
	v_mfma_f32_16x16x32_bf16 v[44:47], v[222:225], v[178:181], v[44:47]
	v_mfma_f32_16x16x32_bf16 v[40:43], v[128:131], v[178:181], v[40:43]
	v_mfma_f32_16x16x32_bf16 v[60:63], v[222:225], v[190:193], v[60:63]
	v_mfma_f32_16x16x32_bf16 v[56:59], v[128:131], v[190:193], v[56:59]
	v_mov_b32_e32 v186, v148
	v_mov_b32_e32 v188, v146
	s_barrier
	ds_read_b128 v[158:161], v153 offset:49152
	ds_read_b128 v[162:165], v153 offset:50176
	ds_read_b128 v[166:169], v153 offset:51200
	ds_read_b128 v[170:173], v153 offset:52224
	ds_read_b128 v[174:177], v153 offset:53248
	ds_read_b128 v[178:181], v153 offset:54272
	ds_read_b128 v[182:185], v153 offset:55296
	ds_read_b128 v[190:193], v153 offset:56320
	v_mov_b32_e32 v187, v189
	v_lshl_add_u64 v[194:195], s[18:19], 0, v[188:189]
	s_mov_b32 m0, s36
	v_lshl_add_u64 v[194:195], v[194:195], 0, s[6:7]
	v_lshl_add_u64 v[186:187], s[18:19], 0, v[186:187]
	global_load_lds_dwordx4 v[194:195], off
	v_lshl_add_u64 v[186:187], v[186:187], 0, s[6:7]
	s_mov_b32 m0, s37
	s_nop 0
	global_load_lds_dwordx4 v[186:187], off
	s_barrier
	s_waitcnt lgkmcnt(0)
	s_waitcnt lgkmcnt(0)
	v_mfma_f32_16x16x32_bf16 v[68:71], v[132:135], v[158:161], v[68:71]
	v_mfma_f32_16x16x32_bf16 v[64:67], v[142:145], v[158:161], v[64:67]
	v_mfma_f32_16x16x32_bf16 v[84:87], v[132:135], v[166:169], v[84:87]
	v_mfma_f32_16x16x32_bf16 v[80:83], v[142:145], v[166:169], v[80:83]
	v_mfma_f32_16x16x32_bf16 v[100:103], v[132:135], v[174:177], v[100:103]
	v_mfma_f32_16x16x32_bf16 v[96:99], v[142:145], v[174:177], v[96:99]
	v_mfma_f32_16x16x32_bf16 v[120:123], v[132:135], v[182:185], v[120:123]
	v_mfma_f32_16x16x32_bf16 v[116:119], v[142:145], v[182:185], v[116:119]
	v_mfma_f32_16x16x32_bf16 v[68:71], v[138:141], v[162:165], v[68:71]
	v_mfma_f32_16x16x32_bf16 v[64:67], v[154:157], v[162:165], v[64:67]
	v_mfma_f32_16x16x32_bf16 v[84:87], v[138:141], v[170:173], v[84:87]
	v_mfma_f32_16x16x32_bf16 v[80:83], v[154:157], v[170:173], v[80:83]
	v_mfma_f32_16x16x32_bf16 v[100:103], v[138:141], v[178:181], v[100:103]
	v_mfma_f32_16x16x32_bf16 v[96:99], v[154:157], v[178:181], v[96:99]
	v_mfma_f32_16x16x32_bf16 v[120:123], v[138:141], v[190:193], v[120:123]
	v_mfma_f32_16x16x32_bf16 v[116:119], v[154:157], v[190:193], v[116:119]
	s_barrier
;     __device__ __forceinline__ void operator()(f32x4 (&acc)[2][2][4][2], const Unit& u, int wr, int wc, int fr, int fq) const {
;     ...
;         const bool fin = (u.br == 2);
;         const int tidl = (wr * 4 + wc) * 64 + fq * 16 + fr;
;         const u32x4* gn = GT + ((size_t)((u.br * 64 + u.pm) * 4 + u.pn) * 16) * 512 + tidl;
;         const u32x4* gd = gn + (size_t)64 * 4 * 16 * 512;
; #pragma unroll
;         for (int ai = 0; ai < 2; ++ai)
; #pragma unroll
;             for (int m = 0; m < 4; ++m) { const size_t row = (size_t)(row0 + ai * HALF + m * 16);
; #pragma unroll
;                 for (int bj = 0; bj < 2; ++bj) { const size_t so = (size_t)((ai * 4 + m) * 2 + bj) * 512;
;                     const u32x4 zn = gn[so]; u32x4 zd = zn; if (!fin) zd = gd[so];
	s_add_u32 s6, s20, 0x20080
	v_mov_b32_e32 v132, v149
	v_mov_b32_e32 v133, v147
	s_addc_u32 s7, s21, 0
	s_mov_b32 m0, s22
	s_nop 0
	global_load_lds_dwordx4 v133, s[6:7]
	s_mov_b32 m0, s23
	s_nop 0
	global_load_lds_dwordx4 v132, s[6:7]
	s_waitcnt vmcnt(6)
	s_barrier
	v_mfma_f32_16x16x32_bf16 v[76:79], v[202:205], v[158:161], v[76:79]
	v_mfma_f32_16x16x32_bf16 v[72:75], v[226:229], v[158:161], v[72:75]
	v_mfma_f32_16x16x32_bf16 v[92:95], v[202:205], v[166:169], v[92:95]
	v_mfma_f32_16x16x32_bf16 v[88:91], v[226:229], v[166:169], v[88:91]
	v_mfma_f32_16x16x32_bf16 v[108:111], v[202:205], v[174:177], v[108:111]
	v_mfma_f32_16x16x32_bf16 v[104:107], v[226:229], v[174:177], v[104:107]
	v_mfma_f32_16x16x32_bf16 v[124:127], v[202:205], v[182:185], v[124:127]
	v_mfma_f32_16x16x32_bf16 v[112:115], v[226:229], v[182:185], v[112:115]
	v_mfma_f32_16x16x32_bf16 v[76:79], v[222:225], v[162:165], v[76:79]
	v_mfma_f32_16x16x32_bf16 v[72:75], v[128:131], v[162:165], v[72:75]
	v_mfma_f32_16x16x32_bf16 v[92:95], v[222:225], v[170:173], v[92:95]
	v_mfma_f32_16x16x32_bf16 v[88:91], v[128:131], v[170:173], v[88:91]
	v_mfma_f32_16x16x32_bf16 v[108:111], v[222:225], v[178:181], v[108:111]
	v_mfma_f32_16x16x32_bf16 v[104:107], v[128:131], v[178:181], v[104:107]
	v_mfma_f32_16x16x32_bf16 v[124:127], v[222:225], v[190:193], v[124:127]
	v_mfma_f32_16x16x32_bf16 v[112:115], v[128:131], v[190:193], v[112:115]
	s_cmp_eq_u32 s42, 2
	s_cselect_b64 s[6:7], -1, 0
	s_cmp_lg_u32 s42, 2
	s_cselect_b64 s[22:23], -1, 0
	s_lshl_b32 s9, s41, 2
	s_lshl_b32 s8, s42, 8
	s_add_i32 s9, s9, s33
	s_add_i32 s8, s9, s8
	s_ashr_i32 s9, s8, 31
	s_lshl_b64 s[8:9], s[8:9], 17
	v_lshl_add_u64 v[138:139], v[136:137], 0, s[8:9]
	s_barrier
	v_mov_b32_e32 v200, 0x2000000
	v_mov_b32_e32 v201, 0
	v_cndmask_b32_e64 v200, v200, 0, s[6:7]
	global_load_dwordx4 v[156:159], v[138:139], off nt
	v_lshl_add_u64 v[198:199], v[138:139], 0, v[200:201]
	global_load_dwordx4 v[160:163], v[198:199], off nt
	v_add_co_u32_e32 v198, vcc, 0x2000, v138
	s_nop 1
	v_addc_co_u32_e32 v199, vcc, 0, v139, vcc
	global_load_dwordx4 v[164:167], v[198:199], off nt
	v_lshl_add_u64 v[198:199], v[198:199], 0, v[200:201]
	global_load_dwordx4 v[168:171], v[198:199], off nt
	v_add_co_u32_e32 v198, vcc, 0x4000, v138
	s_nop 1
	v_addc_co_u32_e32 v199, vcc, 0, v139, vcc
	global_load_dwordx4 v[172:175], v[198:199], off nt
	v_lshl_add_u64 v[198:199], v[198:199], 0, v[200:201]
	global_load_dwordx4 v[176:179], v[198:199], off nt
	v_add_co_u32_e32 v198, vcc, 0x6000, v138
	s_nop 1
	v_addc_co_u32_e32 v199, vcc, 0, v139, vcc
	global_load_dwordx4 v[180:183], v[198:199], off nt
	v_lshl_add_u64 v[198:199], v[198:199], 0, v[200:201]
	global_load_dwordx4 v[184:187], v[198:199], off nt
	v_add_co_u32_e32 v198, vcc, 0x8000, v138
	s_nop 1
	v_addc_co_u32_e32 v199, vcc, 0, v139, vcc
	global_load_dwordx4 v[226:229], v[198:199], off nt
	v_lshl_add_u64 v[198:199], v[198:199], 0, v[200:201]
	global_load_dwordx4 v[230:233], v[198:199], off nt
	v_add_co_u32_e32 v198, vcc, 0xa000, v138
	s_nop 1
	v_addc_co_u32_e32 v199, vcc, 0, v139, vcc
	global_load_dwordx4 v[234:237], v[198:199], off nt
	v_lshl_add_u64 v[198:199], v[198:199], 0, v[200:201]
	global_load_dwordx4 v[238:241], v[198:199], off nt
	v_add_co_u32_e32 v198, vcc, 0xc000, v138
	s_nop 1
	v_addc_co_u32_e32 v199, vcc, 0, v139, vcc
	global_load_dwordx4 v[242:245], v[198:199], off nt
	v_lshl_add_u64 v[198:199], v[198:199], 0, v[200:201]
	global_load_dwordx4 v[246:249], v[198:199], off nt
	v_add_co_u32_e32 v198, vcc, 0xe000, v138
	s_nop 1
	v_addc_co_u32_e32 v199, vcc, 0, v139, vcc
	global_load_dwordx4 v[202:205], v[198:199], off nt
	v_lshl_add_u64 v[198:199], v[198:199], 0, v[200:201]
	global_load_dwordx4 v[194:197], v[198:199], off nt
	s_waitcnt vmcnt(14)
	v_mov_b64_e32 v[128:129], v[156:157]
	v_mov_b64_e32 v[130:131], v[158:159]
	s_and_b64 vcc, exec, s[6:7]
	v_mov_b64_e32 v[132:133], v[160:161]
	v_mov_b64_e32 v[134:135], v[162:163]
	v_add_co_u32_e32 v198, vcc, 0x10000, v138
	s_nop 1
	v_addc_co_u32_e32 v199, vcc, 0, v139, vcc
	global_load_dwordx4 v[156:159], v[198:199], off nt
	v_lshl_add_u64 v[198:199], v[198:199], 0, v[200:201]
	global_load_dwordx4 v[160:163], v[198:199], off nt

;     __device__ __forceinline__ void operator()(f32x4 (&acc)[2][2][4][2], const Unit& u, int wr, int wc, int fr, int fq) const {
;     ...
;                 for (int bj = 0; bj < 2; ++bj) { const size_t so = (size_t)((ai * 4 + m) * 2 + bj) * 512;
;                     const u32x4 zn = gn[so]; u32x4 zd = zn; if (!fin) zd = gd[so];
.LBB0_362:
	s_nop 1
	v_add_co_u32_e32 v128, vcc, 0x2000, v138
	v_cndmask_b32_e64 v132, 0, 1, s[22:23]
	s_nop 0
	v_addc_co_u32_e32 v129, vcc, 0, v139, vcc
	s_waitcnt vmcnt(14)
	v_mov_b64_e32 v[128:129], v[164:165]
	v_mov_b64_e32 v[130:131], v[166:167]
	v_cmp_ne_u32_e64 s[10:11], 1, v132
	v_readlane_b32 s66, v255, 21
	s_andn2_b64 vcc, exec, s[22:23]
	v_readlane_b32 s67, v255, 22
	v_mov_b64_e32 v[132:133], v[168:169]
	v_mov_b64_e32 v[134:135], v[170:171]
	v_add_co_u32_e32 v198, vcc, 0x12000, v138
	s_nop 1
	v_addc_co_u32_e32 v199, vcc, 0, v139, vcc
	global_load_dwordx4 v[164:167], v[198:199], off nt
	v_lshl_add_u64 v[198:199], v[198:199], 0, v[200:201]
	global_load_dwordx4 v[168:171], v[198:199], off nt

;     __device__ __forceinline__ void operator()(f32x4 (&acc)[2][2][4][2], const Unit& u, int wr, int wc, int fr, int fq) const {
;     ...
;                 for (int bj = 0; bj < 2; ++bj) { const size_t so = (size_t)((ai * 4 + m) * 2 + bj) * 512;
;                     const u32x4 zn = gn[so]; u32x4 zd = zn; if (!fin) zd = gd[so];
.LBB0_366:
	s_nop 1
	v_add_co_u32_e32 v128, vcc, 0x4000, v138
	s_nop 1
	v_addc_co_u32_e32 v129, vcc, 0, v139, vcc
	s_waitcnt vmcnt(14)
	v_mov_b64_e32 v[128:129], v[172:173]
	v_mov_b64_e32 v[130:131], v[174:175]
	s_and_b64 vcc, exec, s[10:11]
	v_mov_b64_e32 v[132:133], v[176:177]
	v_mov_b64_e32 v[134:135], v[178:179]
	v_add_co_u32_e32 v198, vcc, 0x14000, v138
	s_nop 1
	v_addc_co_u32_e32 v199, vcc, 0, v139, vcc
	global_load_dwordx4 v[172:175], v[198:199], off nt
	v_lshl_add_u64 v[198:199], v[198:199], 0, v[200:201]
	global_load_dwordx4 v[176:179], v[198:199], off nt

;     __device__ __forceinline__ void operator()(f32x4 (&acc)[2][2][4][2], const Unit& u, int wr, int wc, int fr, int fq) const {
;     ...
;                 for (int bj = 0; bj < 2; ++bj) { const size_t so = (size_t)((ai * 4 + m) * 2 + bj) * 512;
;                     const u32x4 zn = gn[so]; u32x4 zd = zn; if (!fin) zd = gd[so];
.LBB0_370:
	s_nop 1
	v_add_co_u32_e32 v128, vcc, 0x6000, v138
	s_nop 1
	v_addc_co_u32_e32 v129, vcc, 0, v139, vcc
	s_waitcnt vmcnt(14)
	v_mov_b64_e32 v[128:129], v[180:181]
	v_mov_b64_e32 v[130:131], v[182:183]
	s_and_b64 vcc, exec, s[10:11]
	v_mov_b64_e32 v[132:133], v[184:185]
	v_mov_b64_e32 v[134:135], v[186:187]
	v_add_co_u32_e32 v198, vcc, 0x16000, v138
	s_nop 1
	v_addc_co_u32_e32 v199, vcc, 0, v139, vcc
	global_load_dwordx4 v[180:183], v[198:199], off nt
	v_lshl_add_u64 v[198:199], v[198:199], 0, v[200:201]
	global_load_dwordx4 v[184:187], v[198:199], off nt

;     __device__ __forceinline__ void operator()(f32x4 (&acc)[2][2][4][2], const Unit& u, int wr, int wc, int fr, int fq) const {
;     ...
;                 for (int bj = 0; bj < 2; ++bj) { const size_t so = (size_t)((ai * 4 + m) * 2 + bj) * 512;
;                     const u32x4 zn = gn[so]; u32x4 zd = zn; if (!fin) zd = gd[so];
.LBB0_374:
	s_nop 1
	v_add_co_u32_e32 v128, vcc, 0x8000, v138
	s_nop 1
	v_addc_co_u32_e32 v129, vcc, 0, v139, vcc
	s_waitcnt vmcnt(14)
	v_mov_b64_e32 v[128:129], v[226:227]
	v_mov_b64_e32 v[130:131], v[228:229]
	s_and_b64 vcc, exec, s[10:11]
	v_mov_b64_e32 v[132:133], v[230:231]
	v_mov_b64_e32 v[134:135], v[232:233]
	v_add_co_u32_e32 v198, vcc, 0x18000, v138
	s_nop 1
	v_addc_co_u32_e32 v199, vcc, 0, v139, vcc
	global_load_dwordx4 v[226:229], v[198:199], off nt
	v_lshl_add_u64 v[198:199], v[198:199], 0, v[200:201]
	global_load_dwordx4 v[230:233], v[198:199], off nt

;     __device__ __forceinline__ void operator()(f32x4 (&acc)[2][2][4][2], const Unit& u, int wr, int wc, int fr, int fq) const {
;     ...
;                 for (int bj = 0; bj < 2; ++bj) { const size_t so = (size_t)((ai * 4 + m) * 2 + bj) * 512;
;                     const u32x4 zn = gn[so]; u32x4 zd = zn; if (!fin) zd = gd[so];
.LBB0_378:
	s_nop 1
	v_add_co_u32_e32 v128, vcc, 0xa000, v138
	s_nop 1
	v_addc_co_u32_e32 v129, vcc, 0, v139, vcc
	s_waitcnt vmcnt(14)
	v_mov_b64_e32 v[128:129], v[234:235]
	v_mov_b64_e32 v[130:131], v[236:237]
	s_and_b64 vcc, exec, s[10:11]
	v_mov_b64_e32 v[132:133], v[238:239]
	v_mov_b64_e32 v[134:135], v[240:241]
	v_add_co_u32_e32 v198, vcc, 0x1a000, v138
	s_nop 1
	v_addc_co_u32_e32 v199, vcc, 0, v139, vcc
	global_load_dwordx4 v[234:237], v[198:199], off nt
	v_lshl_add_u64 v[198:199], v[198:199], 0, v[200:201]
	global_load_dwordx4 v[238:241], v[198:199], off nt
